# CV1/CV2 on the f32 matrix core: one wave per 16 rows x 16 batches tile, 256 v_mfma_f32_16x16x4_f32 (bf16 weights widened to f32, f32 accumulate)
# speedup vs baseline: 1.0035x; 1.0035x over previous
.LBB0_443:
	v_readlane_b32 s0, v254, 8
	v_readlane_b32 s1, v254, 9
	v_readlane_b32 s2, v254, 20
	v_mbcnt_lo_u32_b32 v0, -1, 0
	v_mbcnt_hi_u32_b32 v0, -1, v0
	s_and_b32 s3, s2, 7
	s_cmp_gt_u32 s69, 1
	s_cbranch_scc1 .Lcv10_idle
	s_cmpk_gt_u32 s2, 0xf7
	s_cbranch_scc1 .Lcv10_idle
	s_lshl_b32 s5, s2, 1
	s_add_i32 s5, s5, s69
	s_add_i32 s8, s5, 0xffffff70
	s_mov_b32 s10, 0x2100000
	s_mov_b32 s11, 0x3200000
	s_mov_b32 s22, 0x3e00000
	s_mov_b32 s23, 0x3d00000
	s_movk_i32 s28, 0x1600
	s_movk_i32 s29, 0x900
	s_movk_i32 s4, 0x6000
	s_movk_i32 s9, 0x3000
	s_cmpk_lt_u32 s5, 0x90
	s_cselect_b32 s8, s5, s8
	s_cselect_b32 s10, s11, s10
	s_cselect_b32 s22, s23, s22
	s_cselect_b32 s23, s29, s28
	s_cselect_b32 s4, s9, s4
	s_lshl_b32 s91, s8, 4
	s_lshl_b32 s8, s8, 15
	s_add_u32 s28, s0, s10
	s_addc_u32 s29, s1, 0
	s_add_u32 s28, s28, s8
	s_addc_u32 s29, s29, 0
	s_add_u32 s10, s0, 0x100000
	s_addc_u32 s11, s1, 0
	s_add_u32 s10, s10, s4
	s_addc_u32 s11, s11, 0
	v_and_b32_e32 v9, 15, v0
	v_lshrrev_b32_e32 v10, 4, v0
	v_lshlrev_b32_e32 v1, 11, v9
	v_lshl_add_u32 v1, v10, 4, v1
	v_mul_u32_u24_e32 v4, 0x9000, v9
	v_lshl_add_u32 v4, v10, 5, v4
	v_mov_b32_e32 v212, 0
	v_mov_b32_e32 v213, 0
	v_mov_b32_e32 v214, 0
	v_mov_b32_e32 v215, 0
	v_mov_b32_e32 v216, 0
	v_mov_b32_e32 v217, 0
	v_mov_b32_e32 v218, 0
	v_mov_b32_e32 v219, 0
	global_load_dwordx4 v[98:101], v1, s[28:29]
	global_load_dwordx4 v[114:117], v4, s[10:11]
	global_load_dwordx4 v[118:121], v4, s[10:11] offset:16
	global_load_dwordx4 v[102:105], v1, s[28:29] offset:64
	global_load_dwordx4 v[122:125], v4, s[10:11] offset:128
	global_load_dwordx4 v[126:129], v4, s[10:11] offset:144
	global_load_dwordx4 v[106:109], v1, s[28:29] offset:128
	global_load_dwordx4 v[130:133], v4, s[10:11] offset:256
	global_load_dwordx4 v[134:137], v4, s[10:11] offset:272
	global_load_dwordx4 v[110:113], v1, s[28:29] offset:192
	global_load_dwordx4 v[138:141], v4, s[10:11] offset:384
	global_load_dwordx4 v[142:145], v4, s[10:11] offset:400
	global_load_dwordx4 v[146:149], v1, s[28:29] offset:256
	global_load_dwordx4 v[162:165], v4, s[10:11] offset:512
	global_load_dwordx4 v[166:169], v4, s[10:11] offset:528
	global_load_dwordx4 v[150:153], v1, s[28:29] offset:320
	global_load_dwordx4 v[170:173], v4, s[10:11] offset:640
	global_load_dwordx4 v[174:177], v4, s[10:11] offset:656
	global_load_dwordx4 v[154:157], v1, s[28:29] offset:384
	global_load_dwordx4 v[178:181], v4, s[10:11] offset:768
	global_load_dwordx4 v[182:185], v4, s[10:11] offset:784
	global_load_dwordx4 v[158:161], v1, s[28:29] offset:448
	global_load_dwordx4 v[186:189], v4, s[10:11] offset:896
	global_load_dwordx4 v[190:193], v4, s[10:11] offset:912
	global_load_dwordx4 v[16:19], v1, s[28:29] offset:512
	global_load_dwordx4 v[32:35], v4, s[10:11] offset:1024
	global_load_dwordx4 v[36:39], v4, s[10:11] offset:1040
	global_load_dwordx4 v[20:23], v1, s[28:29] offset:576
	global_load_dwordx4 v[40:43], v4, s[10:11] offset:1152
	global_load_dwordx4 v[44:47], v4, s[10:11] offset:1168
	global_load_dwordx4 v[24:27], v1, s[28:29] offset:640
	global_load_dwordx4 v[48:51], v4, s[10:11] offset:1280
	global_load_dwordx4 v[52:55], v4, s[10:11] offset:1296
	global_load_dwordx4 v[28:31], v1, s[28:29] offset:704
	global_load_dwordx4 v[56:59], v4, s[10:11] offset:1408
	global_load_dwordx4 v[60:63], v4, s[10:11] offset:1424
	s_waitcnt vmcnt(36)
	s_lshl_b32 s8, s3, 8
	s_add_u32 s8, s0, s8
	s_addc_u32 s9, s1, 0
	v_mov_b32_e32 v15, 0
	v_mov_b32_e32 v11, 1
	s_mov_b64 exec, 1
	global_atomic_add v15, v11, s[8:9] offset:2112
	s_mov_b64 exec, -1
	s_nop 4
	s_waitcnt vmcnt(25)
	v_lshlrev_b32_e32 v194, 16, v98
	v_and_b32_e32 v195, 0xffff0000, v98
	v_lshlrev_b32_e32 v196, 16, v99
	v_and_b32_e32 v197, 0xffff0000, v99
	v_lshlrev_b32_e32 v198, 16, v100
	v_and_b32_e32 v199, 0xffff0000, v100
	v_lshlrev_b32_e32 v200, 16, v101
	v_and_b32_e32 v201, 0xffff0000, v101
	s_nop 1
	v_mfma_f32_16x16x4_f32 v[212:215], v114, v194, v[212:215]
	v_lshlrev_b32_e32 v202, 16, v102
	v_mfma_f32_16x16x4_f32 v[216:219], v115, v195, v[216:219]
	v_and_b32_e32 v203, 0xffff0000, v102
	v_mfma_f32_16x16x4_f32 v[212:215], v116, v196, v[212:215]
	v_lshlrev_b32_e32 v204, 16, v103
	v_mfma_f32_16x16x4_f32 v[216:219], v117, v197, v[216:219]
	v_and_b32_e32 v205, 0xffff0000, v103
	v_mfma_f32_16x16x4_f32 v[212:215], v118, v198, v[212:215]
	v_lshlrev_b32_e32 v206, 16, v104
	v_mfma_f32_16x16x4_f32 v[216:219], v119, v199, v[216:219]
	v_and_b32_e32 v207, 0xffff0000, v104
	v_mfma_f32_16x16x4_f32 v[212:215], v120, v200, v[212:215]
	v_lshlrev_b32_e32 v208, 16, v105
	v_mfma_f32_16x16x4_f32 v[216:219], v121, v201, v[216:219]
	v_and_b32_e32 v209, 0xffff0000, v105
	v_mfma_f32_16x16x4_f32 v[212:215], v122, v202, v[212:215]
	v_lshlrev_b32_e32 v194, 16, v106
	v_mfma_f32_16x16x4_f32 v[216:219], v123, v203, v[216:219]
	v_and_b32_e32 v195, 0xffff0000, v106
	v_mfma_f32_16x16x4_f32 v[212:215], v124, v204, v[212:215]
	v_lshlrev_b32_e32 v196, 16, v107
	v_mfma_f32_16x16x4_f32 v[216:219], v125, v205, v[216:219]
	v_and_b32_e32 v197, 0xffff0000, v107
	v_mfma_f32_16x16x4_f32 v[212:215], v126, v206, v[212:215]
	v_lshlrev_b32_e32 v198, 16, v108
	v_mfma_f32_16x16x4_f32 v[216:219], v127, v207, v[216:219]
	v_and_b32_e32 v199, 0xffff0000, v108
	v_mfma_f32_16x16x4_f32 v[212:215], v128, v208, v[212:215]
	v_lshlrev_b32_e32 v200, 16, v109
	v_mfma_f32_16x16x4_f32 v[216:219], v129, v209, v[216:219]
	v_and_b32_e32 v201, 0xffff0000, v109
	v_mfma_f32_16x16x4_f32 v[212:215], v130, v194, v[212:215]
	v_lshlrev_b32_e32 v202, 16, v110
	v_mfma_f32_16x16x4_f32 v[216:219], v131, v195, v[216:219]
	v_and_b32_e32 v203, 0xffff0000, v110
	v_mfma_f32_16x16x4_f32 v[212:215], v132, v196, v[212:215]
	v_lshlrev_b32_e32 v204, 16, v111
	v_mfma_f32_16x16x4_f32 v[216:219], v133, v197, v[216:219]
	v_and_b32_e32 v205, 0xffff0000, v111
	v_mfma_f32_16x16x4_f32 v[212:215], v134, v198, v[212:215]
	v_lshlrev_b32_e32 v206, 16, v112
	v_mfma_f32_16x16x4_f32 v[216:219], v135, v199, v[216:219]
	v_and_b32_e32 v207, 0xffff0000, v112
	v_mfma_f32_16x16x4_f32 v[212:215], v136, v200, v[212:215]
	v_lshlrev_b32_e32 v208, 16, v113
	v_mfma_f32_16x16x4_f32 v[216:219], v137, v201, v[216:219]
	v_and_b32_e32 v209, 0xffff0000, v113
	v_mfma_f32_16x16x4_f32 v[212:215], v138, v202, v[212:215]
	v_mfma_f32_16x16x4_f32 v[216:219], v139, v203, v[216:219]
	v_mfma_f32_16x16x4_f32 v[212:215], v140, v204, v[212:215]
	v_mfma_f32_16x16x4_f32 v[216:219], v141, v205, v[216:219]
	v_mfma_f32_16x16x4_f32 v[212:215], v142, v206, v[212:215]
	v_mfma_f32_16x16x4_f32 v[216:219], v143, v207, v[216:219]
	v_mfma_f32_16x16x4_f32 v[212:215], v144, v208, v[212:215]
	v_mfma_f32_16x16x4_f32 v[216:219], v145, v209, v[216:219]
	global_load_dwordx4 v[98:101], v1, s[28:29] offset:768
	global_load_dwordx4 v[114:117], v4, s[10:11] offset:1536
	global_load_dwordx4 v[118:121], v4, s[10:11] offset:1552
	global_load_dwordx4 v[102:105], v1, s[28:29] offset:832
	global_load_dwordx4 v[122:125], v4, s[10:11] offset:1664
	global_load_dwordx4 v[126:129], v4, s[10:11] offset:1680
	global_load_dwordx4 v[106:109], v1, s[28:29] offset:896
	global_load_dwordx4 v[130:133], v4, s[10:11] offset:1792
	global_load_dwordx4 v[134:137], v4, s[10:11] offset:1808
	global_load_dwordx4 v[110:113], v1, s[28:29] offset:960
	global_load_dwordx4 v[138:141], v4, s[10:11] offset:1920
	global_load_dwordx4 v[142:145], v4, s[10:11] offset:1936
	s_waitcnt vmcnt(24)
	v_lshlrev_b32_e32 v194, 16, v146
	v_and_b32_e32 v195, 0xffff0000, v146
	v_lshlrev_b32_e32 v196, 16, v147
	v_and_b32_e32 v197, 0xffff0000, v147
	v_lshlrev_b32_e32 v198, 16, v148
	v_and_b32_e32 v199, 0xffff0000, v148
	v_lshlrev_b32_e32 v200, 16, v149
	v_and_b32_e32 v201, 0xffff0000, v149
	s_nop 1
	v_mfma_f32_16x16x4_f32 v[212:215], v162, v194, v[212:215]
	v_lshlrev_b32_e32 v202, 16, v150
	v_mfma_f32_16x16x4_f32 v[216:219], v163, v195, v[216:219]
	v_and_b32_e32 v203, 0xffff0000, v150
	v_mfma_f32_16x16x4_f32 v[212:215], v164, v196, v[212:215]
	v_lshlrev_b32_e32 v204, 16, v151
	v_mfma_f32_16x16x4_f32 v[216:219], v165, v197, v[216:219]
	v_and_b32_e32 v205, 0xffff0000, v151
	v_mfma_f32_16x16x4_f32 v[212:215], v166, v198, v[212:215]
	v_lshlrev_b32_e32 v206, 16, v152
	v_mfma_f32_16x16x4_f32 v[216:219], v167, v199, v[216:219]
	v_and_b32_e32 v207, 0xffff0000, v152
	v_mfma_f32_16x16x4_f32 v[212:215], v168, v200, v[212:215]
	v_lshlrev_b32_e32 v208, 16, v153
	v_mfma_f32_16x16x4_f32 v[216:219], v169, v201, v[216:219]
	v_and_b32_e32 v209, 0xffff0000, v153
	v_mfma_f32_16x16x4_f32 v[212:215], v170, v202, v[212:215]
	v_lshlrev_b32_e32 v194, 16, v154
	v_mfma_f32_16x16x4_f32 v[216:219], v171, v203, v[216:219]
	v_and_b32_e32 v195, 0xffff0000, v154
	v_mfma_f32_16x16x4_f32 v[212:215], v172, v204, v[212:215]
	v_lshlrev_b32_e32 v196, 16, v155
	v_mfma_f32_16x16x4_f32 v[216:219], v173, v205, v[216:219]
	v_and_b32_e32 v197, 0xffff0000, v155
	v_mfma_f32_16x16x4_f32 v[212:215], v174, v206, v[212:215]
	v_lshlrev_b32_e32 v198, 16, v156
	v_mfma_f32_16x16x4_f32 v[216:219], v175, v207, v[216:219]
	v_and_b32_e32 v199, 0xffff0000, v156
	v_mfma_f32_16x16x4_f32 v[212:215], v176, v208, v[212:215]
	v_lshlrev_b32_e32 v200, 16, v157
	v_mfma_f32_16x16x4_f32 v[216:219], v177, v209, v[216:219]
	v_and_b32_e32 v201, 0xffff0000, v157
	v_mfma_f32_16x16x4_f32 v[212:215], v178, v194, v[212:215]
	v_lshlrev_b32_e32 v202, 16, v158
	v_mfma_f32_16x16x4_f32 v[216:219], v179, v195, v[216:219]
	v_and_b32_e32 v203, 0xffff0000, v158
	v_mfma_f32_16x16x4_f32 v[212:215], v180, v196, v[212:215]
	v_lshlrev_b32_e32 v204, 16, v159
	v_mfma_f32_16x16x4_f32 v[216:219], v181, v197, v[216:219]
	v_and_b32_e32 v205, 0xffff0000, v159
	v_mfma_f32_16x16x4_f32 v[212:215], v182, v198, v[212:215]
	v_lshlrev_b32_e32 v206, 16, v160
	v_mfma_f32_16x16x4_f32 v[216:219], v183, v199, v[216:219]
	v_and_b32_e32 v207, 0xffff0000, v160
	v_mfma_f32_16x16x4_f32 v[212:215], v184, v200, v[212:215]
	v_lshlrev_b32_e32 v208, 16, v161
	v_mfma_f32_16x16x4_f32 v[216:219], v185, v201, v[216:219]
	v_and_b32_e32 v209, 0xffff0000, v161
	v_mfma_f32_16x16x4_f32 v[212:215], v186, v202, v[212:215]
	v_mfma_f32_16x16x4_f32 v[216:219], v187, v203, v[216:219]
	v_mfma_f32_16x16x4_f32 v[212:215], v188, v204, v[212:215]
	v_mfma_f32_16x16x4_f32 v[216:219], v189, v205, v[216:219]
	v_mfma_f32_16x16x4_f32 v[212:215], v190, v206, v[212:215]
	v_mfma_f32_16x16x4_f32 v[216:219], v191, v207, v[216:219]
	v_mfma_f32_16x16x4_f32 v[212:215], v192, v208, v[212:215]
	v_mfma_f32_16x16x4_f32 v[216:219], v193, v209, v[216:219]
	global_load_dwordx4 v[146:149], v1, s[28:29] offset:1024
	global_load_dwordx4 v[162:165], v4, s[10:11] offset:2048
	global_load_dwordx4 v[166:169], v4, s[10:11] offset:2064
	global_load_dwordx4 v[150:153], v1, s[28:29] offset:1088
	global_load_dwordx4 v[170:173], v4, s[10:11] offset:2176
	global_load_dwordx4 v[174:177], v4, s[10:11] offset:2192
	global_load_dwordx4 v[154:157], v1, s[28:29] offset:1152
	global_load_dwordx4 v[178:181], v4, s[10:11] offset:2304
	global_load_dwordx4 v[182:185], v4, s[10:11] offset:2320
	global_load_dwordx4 v[158:161], v1, s[28:29] offset:1216
	global_load_dwordx4 v[186:189], v4, s[10:11] offset:2432
	global_load_dwordx4 v[190:193], v4, s[10:11] offset:2448
	s_waitcnt vmcnt(24)
	v_lshlrev_b32_e32 v194, 16, v16
	v_and_b32_e32 v195, 0xffff0000, v16
	v_lshlrev_b32_e32 v196, 16, v17
	v_and_b32_e32 v197, 0xffff0000, v17
	v_lshlrev_b32_e32 v198, 16, v18
	v_and_b32_e32 v199, 0xffff0000, v18
	v_lshlrev_b32_e32 v200, 16, v19
	v_and_b32_e32 v201, 0xffff0000, v19
	s_nop 1
	v_mfma_f32_16x16x4_f32 v[212:215], v32, v194, v[212:215]
	v_lshlrev_b32_e32 v202, 16, v20
	v_mfma_f32_16x16x4_f32 v[216:219], v33, v195, v[216:219]
	v_and_b32_e32 v203, 0xffff0000, v20
	v_mfma_f32_16x16x4_f32 v[212:215], v34, v196, v[212:215]
	v_lshlrev_b32_e32 v204, 16, v21
	v_mfma_f32_16x16x4_f32 v[216:219], v35, v197, v[216:219]
	v_and_b32_e32 v205, 0xffff0000, v21
	v_mfma_f32_16x16x4_f32 v[212:215], v36, v198, v[212:215]
	v_lshlrev_b32_e32 v206, 16, v22
	v_mfma_f32_16x16x4_f32 v[216:219], v37, v199, v[216:219]
	v_and_b32_e32 v207, 0xffff0000, v22
	v_mfma_f32_16x16x4_f32 v[212:215], v38, v200, v[212:215]
	v_lshlrev_b32_e32 v208, 16, v23
	v_mfma_f32_16x16x4_f32 v[216:219], v39, v201, v[216:219]
	v_and_b32_e32 v209, 0xffff0000, v23
	v_mfma_f32_16x16x4_f32 v[212:215], v40, v202, v[212:215]
	v_lshlrev_b32_e32 v194, 16, v24
	v_mfma_f32_16x16x4_f32 v[216:219], v41, v203, v[216:219]
	v_and_b32_e32 v195, 0xffff0000, v24
	v_mfma_f32_16x16x4_f32 v[212:215], v42, v204, v[212:215]
	v_lshlrev_b32_e32 v196, 16, v25
	v_mfma_f32_16x16x4_f32 v[216:219], v43, v205, v[216:219]
	v_and_b32_e32 v197, 0xffff0000, v25
	v_mfma_f32_16x16x4_f32 v[212:215], v44, v206, v[212:215]
	v_lshlrev_b32_e32 v198, 16, v26
	v_mfma_f32_16x16x4_f32 v[216:219], v45, v207, v[216:219]
	v_and_b32_e32 v199, 0xffff0000, v26
	v_mfma_f32_16x16x4_f32 v[212:215], v46, v208, v[212:215]
	v_lshlrev_b32_e32 v200, 16, v27
	v_mfma_f32_16x16x4_f32 v[216:219], v47, v209, v[216:219]
	v_and_b32_e32 v201, 0xffff0000, v27
	v_mfma_f32_16x16x4_f32 v[212:215], v48, v194, v[212:215]
	v_lshlrev_b32_e32 v202, 16, v28
	v_mfma_f32_16x16x4_f32 v[216:219], v49, v195, v[216:219]
	v_and_b32_e32 v203, 0xffff0000, v28
	v_mfma_f32_16x16x4_f32 v[212:215], v50, v196, v[212:215]
	v_lshlrev_b32_e32 v204, 16, v29
	v_mfma_f32_16x16x4_f32 v[216:219], v51, v197, v[216:219]
	v_and_b32_e32 v205, 0xffff0000, v29
	v_mfma_f32_16x16x4_f32 v[212:215], v52, v198, v[212:215]
	v_lshlrev_b32_e32 v206, 16, v30
	v_mfma_f32_16x16x4_f32 v[216:219], v53, v199, v[216:219]
	v_and_b32_e32 v207, 0xffff0000, v30
	v_mfma_f32_16x16x4_f32 v[212:215], v54, v200, v[212:215]
	v_lshlrev_b32_e32 v208, 16, v31
	v_mfma_f32_16x16x4_f32 v[216:219], v55, v201, v[216:219]
	v_and_b32_e32 v209, 0xffff0000, v31
	v_mfma_f32_16x16x4_f32 v[212:215], v56, v202, v[212:215]
	v_mfma_f32_16x16x4_f32 v[216:219], v57, v203, v[216:219]
	v_mfma_f32_16x16x4_f32 v[212:215], v58, v204, v[212:215]
	v_mfma_f32_16x16x4_f32 v[216:219], v59, v205, v[216:219]
	v_mfma_f32_16x16x4_f32 v[212:215], v60, v206, v[212:215]
	v_mfma_f32_16x16x4_f32 v[216:219], v61, v207, v[216:219]
	v_mfma_f32_16x16x4_f32 v[212:215], v62, v208, v[212:215]
	v_mfma_f32_16x16x4_f32 v[216:219], v63, v209, v[216:219]
	global_load_dwordx4 v[16:19], v1, s[28:29] offset:1280
	global_load_dwordx4 v[32:35], v4, s[10:11] offset:2560
	global_load_dwordx4 v[36:39], v4, s[10:11] offset:2576
	global_load_dwordx4 v[20:23], v1, s[28:29] offset:1344
	global_load_dwordx4 v[40:43], v4, s[10:11] offset:2688
	global_load_dwordx4 v[44:47], v4, s[10:11] offset:2704
	global_load_dwordx4 v[24:27], v1, s[28:29] offset:1408
	global_load_dwordx4 v[48:51], v4, s[10:11] offset:2816
	global_load_dwordx4 v[52:55], v4, s[10:11] offset:2832
	global_load_dwordx4 v[28:31], v1, s[28:29] offset:1472
	global_load_dwordx4 v[56:59], v4, s[10:11] offset:2944
	global_load_dwordx4 v[60:63], v4, s[10:11] offset:2960
	s_waitcnt vmcnt(24)
	v_lshlrev_b32_e32 v194, 16, v98
	v_and_b32_e32 v195, 0xffff0000, v98
	v_lshlrev_b32_e32 v196, 16, v99
	v_and_b32_e32 v197, 0xffff0000, v99
	v_lshlrev_b32_e32 v198, 16, v100
	v_and_b32_e32 v199, 0xffff0000, v100
	v_lshlrev_b32_e32 v200, 16, v101
	v_and_b32_e32 v201, 0xffff0000, v101
	s_nop 1
	v_mfma_f32_16x16x4_f32 v[212:215], v114, v194, v[212:215]
	v_lshlrev_b32_e32 v202, 16, v102
	v_mfma_f32_16x16x4_f32 v[216:219], v115, v195, v[216:219]
	v_and_b32_e32 v203, 0xffff0000, v102
	v_mfma_f32_16x16x4_f32 v[212:215], v116, v196, v[212:215]
	v_lshlrev_b32_e32 v204, 16, v103
	v_mfma_f32_16x16x4_f32 v[216:219], v117, v197, v[216:219]
	v_and_b32_e32 v205, 0xffff0000, v103
	v_mfma_f32_16x16x4_f32 v[212:215], v118, v198, v[212:215]
	v_lshlrev_b32_e32 v206, 16, v104
	v_mfma_f32_16x16x4_f32 v[216:219], v119, v199, v[216:219]
	v_and_b32_e32 v207, 0xffff0000, v104
	v_mfma_f32_16x16x4_f32 v[212:215], v120, v200, v[212:215]
	v_lshlrev_b32_e32 v208, 16, v105
	v_mfma_f32_16x16x4_f32 v[216:219], v121, v201, v[216:219]
	v_and_b32_e32 v209, 0xffff0000, v105
	v_mfma_f32_16x16x4_f32 v[212:215], v122, v202, v[212:215]
	v_lshlrev_b32_e32 v194, 16, v106
	v_mfma_f32_16x16x4_f32 v[216:219], v123, v203, v[216:219]
	v_and_b32_e32 v195, 0xffff0000, v106
	v_mfma_f32_16x16x4_f32 v[212:215], v124, v204, v[212:215]
	v_lshlrev_b32_e32 v196, 16, v107
	v_mfma_f32_16x16x4_f32 v[216:219], v125, v205, v[216:219]
	v_and_b32_e32 v197, 0xffff0000, v107
	v_mfma_f32_16x16x4_f32 v[212:215], v126, v206, v[212:215]
	v_lshlrev_b32_e32 v198, 16, v108
	v_mfma_f32_16x16x4_f32 v[216:219], v127, v207, v[216:219]
	v_and_b32_e32 v199, 0xffff0000, v108
	v_mfma_f32_16x16x4_f32 v[212:215], v128, v208, v[212:215]
	v_lshlrev_b32_e32 v200, 16, v109
	v_mfma_f32_16x16x4_f32 v[216:219], v129, v209, v[216:219]
	v_and_b32_e32 v201, 0xffff0000, v109
	v_mfma_f32_16x16x4_f32 v[212:215], v130, v194, v[212:215]
	v_lshlrev_b32_e32 v202, 16, v110
	v_mfma_f32_16x16x4_f32 v[216:219], v131, v195, v[216:219]
	v_and_b32_e32 v203, 0xffff0000, v110
	v_mfma_f32_16x16x4_f32 v[212:215], v132, v196, v[212:215]
	v_lshlrev_b32_e32 v204, 16, v111
	v_mfma_f32_16x16x4_f32 v[216:219], v133, v197, v[216:219]
	v_and_b32_e32 v205, 0xffff0000, v111
	v_mfma_f32_16x16x4_f32 v[212:215], v134, v198, v[212:215]
	v_lshlrev_b32_e32 v206, 16, v112
	v_mfma_f32_16x16x4_f32 v[216:219], v135, v199, v[216:219]
	v_and_b32_e32 v207, 0xffff0000, v112
	v_mfma_f32_16x16x4_f32 v[212:215], v136, v200, v[212:215]
	v_lshlrev_b32_e32 v208, 16, v113
	v_mfma_f32_16x16x4_f32 v[216:219], v137, v201, v[216:219]
	v_and_b32_e32 v209, 0xffff0000, v113
	v_mfma_f32_16x16x4_f32 v[212:215], v138, v202, v[212:215]
	v_mfma_f32_16x16x4_f32 v[216:219], v139, v203, v[216:219]
	v_mfma_f32_16x16x4_f32 v[212:215], v140, v204, v[212:215]
	v_mfma_f32_16x16x4_f32 v[216:219], v141, v205, v[216:219]
	v_mfma_f32_16x16x4_f32 v[212:215], v142, v206, v[212:215]
	v_mfma_f32_16x16x4_f32 v[216:219], v143, v207, v[216:219]
	v_mfma_f32_16x16x4_f32 v[212:215], v144, v208, v[212:215]
	v_mfma_f32_16x16x4_f32 v[216:219], v145, v209, v[216:219]
	global_load_dwordx4 v[98:101], v1, s[28:29] offset:1536
	global_load_dwordx4 v[114:117], v4, s[10:11] offset:3072
	global_load_dwordx4 v[118:121], v4, s[10:11] offset:3088
	global_load_dwordx4 v[102:105], v1, s[28:29] offset:1600
	global_load_dwordx4 v[122:125], v4, s[10:11] offset:3200
	global_load_dwordx4 v[126:129], v4, s[10:11] offset:3216
	global_load_dwordx4 v[106:109], v1, s[28:29] offset:1664
	global_load_dwordx4 v[130:133], v4, s[10:11] offset:3328
	global_load_dwordx4 v[134:137], v4, s[10:11] offset:3344
	global_load_dwordx4 v[110:113], v1, s[28:29] offset:1728
	global_load_dwordx4 v[138:141], v4, s[10:11] offset:3456
	global_load_dwordx4 v[142:145], v4, s[10:11] offset:3472
	s_waitcnt vmcnt(24)
	v_lshlrev_b32_e32 v194, 16, v146
	v_and_b32_e32 v195, 0xffff0000, v146
	v_lshlrev_b32_e32 v196, 16, v147
	v_and_b32_e32 v197, 0xffff0000, v147
	v_lshlrev_b32_e32 v198, 16, v148
	v_and_b32_e32 v199, 0xffff0000, v148
	v_lshlrev_b32_e32 v200, 16, v149
	v_and_b32_e32 v201, 0xffff0000, v149
	s_nop 1
	v_mfma_f32_16x16x4_f32 v[212:215], v162, v194, v[212:215]
	v_lshlrev_b32_e32 v202, 16, v150
	v_mfma_f32_16x16x4_f32 v[216:219], v163, v195, v[216:219]
	v_and_b32_e32 v203, 0xffff0000, v150
	v_mfma_f32_16x16x4_f32 v[212:215], v164, v196, v[212:215]
	v_lshlrev_b32_e32 v204, 16, v151
	v_mfma_f32_16x16x4_f32 v[216:219], v165, v197, v[216:219]
	v_and_b32_e32 v205, 0xffff0000, v151
	v_mfma_f32_16x16x4_f32 v[212:215], v166, v198, v[212:215]
	v_lshlrev_b32_e32 v206, 16, v152
	v_mfma_f32_16x16x4_f32 v[216:219], v167, v199, v[216:219]
	v_and_b32_e32 v207, 0xffff0000, v152
	v_mfma_f32_16x16x4_f32 v[212:215], v168, v200, v[212:215]
	v_lshlrev_b32_e32 v208, 16, v153
	v_mfma_f32_16x16x4_f32 v[216:219], v169, v201, v[216:219]
	v_and_b32_e32 v209, 0xffff0000, v153
	v_mfma_f32_16x16x4_f32 v[212:215], v170, v202, v[212:215]
	v_lshlrev_b32_e32 v194, 16, v154
	v_mfma_f32_16x16x4_f32 v[216:219], v171, v203, v[216:219]
	v_and_b32_e32 v195, 0xffff0000, v154
	v_mfma_f32_16x16x4_f32 v[212:215], v172, v204, v[212:215]
	v_lshlrev_b32_e32 v196, 16, v155
	v_mfma_f32_16x16x4_f32 v[216:219], v173, v205, v[216:219]
	v_and_b32_e32 v197, 0xffff0000, v155
	v_mfma_f32_16x16x4_f32 v[212:215], v174, v206, v[212:215]
	v_lshlrev_b32_e32 v198, 16, v156
	v_mfma_f32_16x16x4_f32 v[216:219], v175, v207, v[216:219]
	v_and_b32_e32 v199, 0xffff0000, v156
	v_mfma_f32_16x16x4_f32 v[212:215], v176, v208, v[212:215]
	v_lshlrev_b32_e32 v200, 16, v157
	v_mfma_f32_16x16x4_f32 v[216:219], v177, v209, v[216:219]
	v_and_b32_e32 v201, 0xffff0000, v157
	v_mfma_f32_16x16x4_f32 v[212:215], v178, v194, v[212:215]
	v_lshlrev_b32_e32 v202, 16, v158
	v_mfma_f32_16x16x4_f32 v[216:219], v179, v195, v[216:219]
	v_and_b32_e32 v203, 0xffff0000, v158
	v_mfma_f32_16x16x4_f32 v[212:215], v180, v196, v[212:215]
	v_lshlrev_b32_e32 v204, 16, v159
	v_mfma_f32_16x16x4_f32 v[216:219], v181, v197, v[216:219]
	v_and_b32_e32 v205, 0xffff0000, v159
	v_mfma_f32_16x16x4_f32 v[212:215], v182, v198, v[212:215]
	v_lshlrev_b32_e32 v206, 16, v160
	v_mfma_f32_16x16x4_f32 v[216:219], v183, v199, v[216:219]
	v_and_b32_e32 v207, 0xffff0000, v160
	v_mfma_f32_16x16x4_f32 v[212:215], v184, v200, v[212:215]
	v_lshlrev_b32_e32 v208, 16, v161
	v_mfma_f32_16x16x4_f32 v[216:219], v185, v201, v[216:219]
	v_and_b32_e32 v209, 0xffff0000, v161
	v_mfma_f32_16x16x4_f32 v[212:215], v186, v202, v[212:215]
	v_mfma_f32_16x16x4_f32 v[216:219], v187, v203, v[216:219]
	v_mfma_f32_16x16x4_f32 v[212:215], v188, v204, v[212:215]
	v_mfma_f32_16x16x4_f32 v[216:219], v189, v205, v[216:219]
	v_mfma_f32_16x16x4_f32 v[212:215], v190, v206, v[212:215]
	v_mfma_f32_16x16x4_f32 v[216:219], v191, v207, v[216:219]
	v_mfma_f32_16x16x4_f32 v[212:215], v192, v208, v[212:215]
	v_mfma_f32_16x16x4_f32 v[216:219], v193, v209, v[216:219]
	global_load_dwordx4 v[146:149], v1, s[28:29] offset:1792
	global_load_dwordx4 v[162:165], v4, s[10:11] offset:3584
	global_load_dwordx4 v[166:169], v4, s[10:11] offset:3600
	global_load_dwordx4 v[150:153], v1, s[28:29] offset:1856
	global_load_dwordx4 v[170:173], v4, s[10:11] offset:3712
	global_load_dwordx4 v[174:177], v4, s[10:11] offset:3728
	global_load_dwordx4 v[154:157], v1, s[28:29] offset:1920
	global_load_dwordx4 v[178:181], v4, s[10:11] offset:3840
	global_load_dwordx4 v[182:185], v4, s[10:11] offset:3856
	global_load_dwordx4 v[158:161], v1, s[28:29] offset:1984
	global_load_dwordx4 v[186:189], v4, s[10:11] offset:3968
	global_load_dwordx4 v[190:193], v4, s[10:11] offset:3984
	s_waitcnt vmcnt(24)
	v_lshlrev_b32_e32 v194, 16, v16
	v_and_b32_e32 v195, 0xffff0000, v16
	v_lshlrev_b32_e32 v196, 16, v17
	v_and_b32_e32 v197, 0xffff0000, v17
	v_lshlrev_b32_e32 v198, 16, v18
	v_and_b32_e32 v199, 0xffff0000, v18
	v_lshlrev_b32_e32 v200, 16, v19
	v_and_b32_e32 v201, 0xffff0000, v19
	s_nop 1
	v_mfma_f32_16x16x4_f32 v[212:215], v32, v194, v[212:215]
	v_lshlrev_b32_e32 v202, 16, v20
	v_mfma_f32_16x16x4_f32 v[216:219], v33, v195, v[216:219]
	v_and_b32_e32 v203, 0xffff0000, v20
	v_mfma_f32_16x16x4_f32 v[212:215], v34, v196, v[212:215]
	v_lshlrev_b32_e32 v204, 16, v21
	v_mfma_f32_16x16x4_f32 v[216:219], v35, v197, v[216:219]
	v_and_b32_e32 v205, 0xffff0000, v21
	v_mfma_f32_16x16x4_f32 v[212:215], v36, v198, v[212:215]
	v_lshlrev_b32_e32 v206, 16, v22
	v_mfma_f32_16x16x4_f32 v[216:219], v37, v199, v[216:219]
	v_and_b32_e32 v207, 0xffff0000, v22
	v_mfma_f32_16x16x4_f32 v[212:215], v38, v200, v[212:215]
	v_lshlrev_b32_e32 v208, 16, v23
	v_mfma_f32_16x16x4_f32 v[216:219], v39, v201, v[216:219]
	v_and_b32_e32 v209, 0xffff0000, v23
	v_mfma_f32_16x16x4_f32 v[212:215], v40, v202, v[212:215]
	v_lshlrev_b32_e32 v194, 16, v24
	v_mfma_f32_16x16x4_f32 v[216:219], v41, v203, v[216:219]
	v_and_b32_e32 v195, 0xffff0000, v24
	v_mfma_f32_16x16x4_f32 v[212:215], v42, v204, v[212:215]
	v_lshlrev_b32_e32 v196, 16, v25
	v_mfma_f32_16x16x4_f32 v[216:219], v43, v205, v[216:219]
	v_and_b32_e32 v197, 0xffff0000, v25
	v_mfma_f32_16x16x4_f32 v[212:215], v44, v206, v[212:215]
	v_lshlrev_b32_e32 v198, 16, v26
	v_mfma_f32_16x16x4_f32 v[216:219], v45, v207, v[216:219]
	v_and_b32_e32 v199, 0xffff0000, v26
	v_mfma_f32_16x16x4_f32 v[212:215], v46, v208, v[212:215]
	v_lshlrev_b32_e32 v200, 16, v27
	v_mfma_f32_16x16x4_f32 v[216:219], v47, v209, v[216:219]
	v_and_b32_e32 v201, 0xffff0000, v27
	v_mfma_f32_16x16x4_f32 v[212:215], v48, v194, v[212:215]
	v_lshlrev_b32_e32 v202, 16, v28
	v_mfma_f32_16x16x4_f32 v[216:219], v49, v195, v[216:219]
	v_and_b32_e32 v203, 0xffff0000, v28
	v_mfma_f32_16x16x4_f32 v[212:215], v50, v196, v[212:215]
	v_lshlrev_b32_e32 v204, 16, v29
	v_mfma_f32_16x16x4_f32 v[216:219], v51, v197, v[216:219]
	v_and_b32_e32 v205, 0xffff0000, v29
	v_mfma_f32_16x16x4_f32 v[212:215], v52, v198, v[212:215]
	v_lshlrev_b32_e32 v206, 16, v30
	v_mfma_f32_16x16x4_f32 v[216:219], v53, v199, v[216:219]
	v_and_b32_e32 v207, 0xffff0000, v30
	v_mfma_f32_16x16x4_f32 v[212:215], v54, v200, v[212:215]
	v_lshlrev_b32_e32 v208, 16, v31
	v_mfma_f32_16x16x4_f32 v[216:219], v55, v201, v[216:219]
	v_and_b32_e32 v209, 0xffff0000, v31
	v_mfma_f32_16x16x4_f32 v[212:215], v56, v202, v[212:215]
	v_mfma_f32_16x16x4_f32 v[216:219], v57, v203, v[216:219]
	v_mfma_f32_16x16x4_f32 v[212:215], v58, v204, v[212:215]
	v_mfma_f32_16x16x4_f32 v[216:219], v59, v205, v[216:219]
	v_mfma_f32_16x16x4_f32 v[212:215], v60, v206, v[212:215]
	v_mfma_f32_16x16x4_f32 v[216:219], v61, v207, v[216:219]
	v_mfma_f32_16x16x4_f32 v[212:215], v62, v208, v[212:215]
	v_mfma_f32_16x16x4_f32 v[216:219], v63, v209, v[216:219]
	s_waitcnt vmcnt(12)
	v_lshlrev_b32_e32 v194, 16, v98
	v_and_b32_e32 v195, 0xffff0000, v98
	v_lshlrev_b32_e32 v196, 16, v99
	v_and_b32_e32 v197, 0xffff0000, v99
	v_lshlrev_b32_e32 v198, 16, v100
	v_and_b32_e32 v199, 0xffff0000, v100
	v_lshlrev_b32_e32 v200, 16, v101
	v_and_b32_e32 v201, 0xffff0000, v101
	s_nop 1
	v_mfma_f32_16x16x4_f32 v[212:215], v114, v194, v[212:215]
	v_lshlrev_b32_e32 v202, 16, v102
	v_mfma_f32_16x16x4_f32 v[216:219], v115, v195, v[216:219]
	v_and_b32_e32 v203, 0xffff0000, v102
	v_mfma_f32_16x16x4_f32 v[212:215], v116, v196, v[212:215]
	v_lshlrev_b32_e32 v204, 16, v103
	v_mfma_f32_16x16x4_f32 v[216:219], v117, v197, v[216:219]
	v_and_b32_e32 v205, 0xffff0000, v103
	v_mfma_f32_16x16x4_f32 v[212:215], v118, v198, v[212:215]
	v_lshlrev_b32_e32 v206, 16, v104
	v_mfma_f32_16x16x4_f32 v[216:219], v119, v199, v[216:219]
	v_and_b32_e32 v207, 0xffff0000, v104
	v_mfma_f32_16x16x4_f32 v[212:215], v120, v200, v[212:215]
	v_lshlrev_b32_e32 v208, 16, v105
	v_mfma_f32_16x16x4_f32 v[216:219], v121, v201, v[216:219]
	v_and_b32_e32 v209, 0xffff0000, v105
	v_mfma_f32_16x16x4_f32 v[212:215], v122, v202, v[212:215]
	v_lshlrev_b32_e32 v194, 16, v106
	v_mfma_f32_16x16x4_f32 v[216:219], v123, v203, v[216:219]
	v_and_b32_e32 v195, 0xffff0000, v106
	v_mfma_f32_16x16x4_f32 v[212:215], v124, v204, v[212:215]
	v_lshlrev_b32_e32 v196, 16, v107
	v_mfma_f32_16x16x4_f32 v[216:219], v125, v205, v[216:219]
	v_and_b32_e32 v197, 0xffff0000, v107
	v_mfma_f32_16x16x4_f32 v[212:215], v126, v206, v[212:215]
	v_lshlrev_b32_e32 v198, 16, v108
	v_mfma_f32_16x16x4_f32 v[216:219], v127, v207, v[216:219]
	v_and_b32_e32 v199, 0xffff0000, v108
	v_mfma_f32_16x16x4_f32 v[212:215], v128, v208, v[212:215]
	v_lshlrev_b32_e32 v200, 16, v109
	v_mfma_f32_16x16x4_f32 v[216:219], v129, v209, v[216:219]
	v_and_b32_e32 v201, 0xffff0000, v109
	v_mfma_f32_16x16x4_f32 v[212:215], v130, v194, v[212:215]
	v_lshlrev_b32_e32 v202, 16, v110
	v_mfma_f32_16x16x4_f32 v[216:219], v131, v195, v[216:219]
	v_and_b32_e32 v203, 0xffff0000, v110
	v_mfma_f32_16x16x4_f32 v[212:215], v132, v196, v[212:215]
	v_lshlrev_b32_e32 v204, 16, v111
	v_mfma_f32_16x16x4_f32 v[216:219], v133, v197, v[216:219]
	v_and_b32_e32 v205, 0xffff0000, v111
	v_mfma_f32_16x16x4_f32 v[212:215], v134, v198, v[212:215]
	v_lshlrev_b32_e32 v206, 16, v112
	v_mfma_f32_16x16x4_f32 v[216:219], v135, v199, v[216:219]
	v_and_b32_e32 v207, 0xffff0000, v112
	v_mfma_f32_16x16x4_f32 v[212:215], v136, v200, v[212:215]
	v_lshlrev_b32_e32 v208, 16, v113
	v_mfma_f32_16x16x4_f32 v[216:219], v137, v201, v[216:219]
	v_and_b32_e32 v209, 0xffff0000, v113
	v_mfma_f32_16x16x4_f32 v[212:215], v138, v202, v[212:215]
	v_mfma_f32_16x16x4_f32 v[216:219], v139, v203, v[216:219]
	v_mfma_f32_16x16x4_f32 v[212:215], v140, v204, v[212:215]
	v_mfma_f32_16x16x4_f32 v[216:219], v141, v205, v[216:219]
	v_mfma_f32_16x16x4_f32 v[212:215], v142, v206, v[212:215]
	v_mfma_f32_16x16x4_f32 v[216:219], v143, v207, v[216:219]
	v_mfma_f32_16x16x4_f32 v[212:215], v144, v208, v[212:215]
	v_mfma_f32_16x16x4_f32 v[216:219], v145, v209, v[216:219]
	s_waitcnt vmcnt(0)
	v_lshlrev_b32_e32 v194, 16, v146
	v_and_b32_e32 v195, 0xffff0000, v146
	v_lshlrev_b32_e32 v196, 16, v147
	v_and_b32_e32 v197, 0xffff0000, v147
	v_lshlrev_b32_e32 v198, 16, v148
	v_and_b32_e32 v199, 0xffff0000, v148
	v_lshlrev_b32_e32 v200, 16, v149
	v_and_b32_e32 v201, 0xffff0000, v149
	s_nop 1
	v_mfma_f32_16x16x4_f32 v[212:215], v162, v194, v[212:215]
	v_lshlrev_b32_e32 v202, 16, v150
	v_mfma_f32_16x16x4_f32 v[216:219], v163, v195, v[216:219]
	v_and_b32_e32 v203, 0xffff0000, v150
	v_mfma_f32_16x16x4_f32 v[212:215], v164, v196, v[212:215]
	v_lshlrev_b32_e32 v204, 16, v151
	v_mfma_f32_16x16x4_f32 v[216:219], v165, v197, v[216:219]
	v_and_b32_e32 v205, 0xffff0000, v151
	v_mfma_f32_16x16x4_f32 v[212:215], v166, v198, v[212:215]
	v_lshlrev_b32_e32 v206, 16, v152
	v_mfma_f32_16x16x4_f32 v[216:219], v167, v199, v[216:219]
	v_and_b32_e32 v207, 0xffff0000, v152
	v_mfma_f32_16x16x4_f32 v[212:215], v168, v200, v[212:215]
	v_lshlrev_b32_e32 v208, 16, v153
	v_mfma_f32_16x16x4_f32 v[216:219], v169, v201, v[216:219]
	v_and_b32_e32 v209, 0xffff0000, v153
	v_mfma_f32_16x16x4_f32 v[212:215], v170, v202, v[212:215]
	v_lshlrev_b32_e32 v194, 16, v154
	v_mfma_f32_16x16x4_f32 v[216:219], v171, v203, v[216:219]
	v_and_b32_e32 v195, 0xffff0000, v154
	v_mfma_f32_16x16x4_f32 v[212:215], v172, v204, v[212:215]
	v_lshlrev_b32_e32 v196, 16, v155
	v_mfma_f32_16x16x4_f32 v[216:219], v173, v205, v[216:219]
	v_and_b32_e32 v197, 0xffff0000, v155
	v_mfma_f32_16x16x4_f32 v[212:215], v174, v206, v[212:215]
	v_lshlrev_b32_e32 v198, 16, v156
	v_mfma_f32_16x16x4_f32 v[216:219], v175, v207, v[216:219]
	v_and_b32_e32 v199, 0xffff0000, v156
	v_mfma_f32_16x16x4_f32 v[212:215], v176, v208, v[212:215]
	v_lshlrev_b32_e32 v200, 16, v157
	v_mfma_f32_16x16x4_f32 v[216:219], v177, v209, v[216:219]
	v_and_b32_e32 v201, 0xffff0000, v157
	v_mfma_f32_16x16x4_f32 v[212:215], v178, v194, v[212:215]
	v_lshlrev_b32_e32 v202, 16, v158
	v_mfma_f32_16x16x4_f32 v[216:219], v179, v195, v[216:219]
	v_and_b32_e32 v203, 0xffff0000, v158
	v_mfma_f32_16x16x4_f32 v[212:215], v180, v196, v[212:215]
	v_lshlrev_b32_e32 v204, 16, v159
	v_mfma_f32_16x16x4_f32 v[216:219], v181, v197, v[216:219]
	v_and_b32_e32 v205, 0xffff0000, v159
	v_mfma_f32_16x16x4_f32 v[212:215], v182, v198, v[212:215]
	v_lshlrev_b32_e32 v206, 16, v160
	v_mfma_f32_16x16x4_f32 v[216:219], v183, v199, v[216:219]
	v_and_b32_e32 v207, 0xffff0000, v160
	v_mfma_f32_16x16x4_f32 v[212:215], v184, v200, v[212:215]
	v_lshlrev_b32_e32 v208, 16, v161
	v_mfma_f32_16x16x4_f32 v[216:219], v185, v201, v[216:219]
	v_and_b32_e32 v209, 0xffff0000, v161
	v_mfma_f32_16x16x4_f32 v[212:215], v186, v202, v[212:215]
	v_mfma_f32_16x16x4_f32 v[216:219], v187, v203, v[216:219]
	v_mfma_f32_16x16x4_f32 v[212:215], v188, v204, v[212:215]
	v_mfma_f32_16x16x4_f32 v[216:219], v189, v205, v[216:219]
	v_mfma_f32_16x16x4_f32 v[212:215], v190, v206, v[212:215]
	v_mfma_f32_16x16x4_f32 v[216:219], v191, v207, v[216:219]
	v_mfma_f32_16x16x4_f32 v[212:215], v192, v208, v[212:215]
	v_mfma_f32_16x16x4_f32 v[216:219], v193, v209, v[216:219]
	s_nop 7
	s_nop 7
	v_add_f32_e32 v212, v212, v216
	v_add_f32_e32 v213, v213, v217
	v_add_f32_e32 v214, v214, v218
	v_add_f32_e32 v215, v215, v219
	v_lshlrev_b32_e32 v11, 2, v10
	v_mul_lo_u32 v11, v11, s23
	v_add3_u32 v11, v11, v9, s91
	v_lshlrev_b32_e32 v5, 2, v11
	s_lshl_b32 s4, s23, 2
	v_add_u32_e32 v6, s4, v5
	v_add_u32_e32 v7, s4, v6
	v_add_u32_e32 v8, s4, v7
	s_add_u32 s8, s0, s22
	s_addc_u32 s9, s1, 0
	global_store_dword v5, v212, s[8:9] sc1
	global_store_dword v6, v213, s[8:9] sc1
	global_store_dword v7, v214, s[8:9] sc1
	global_store_dword v8, v215, s[8:9] sc1
	s_branch .LBB0_477
